# P4 conv_branch_a item loop: two items in flight (13+13 loads issued before compute), on top of saddr/preload/movb64 kernel
# speedup vs baseline: 1.0038x; 1.0036x over previous
.LBB0_555:
	v_ashrrev_i32_e32 v6, 8, v12
	v_and_b32_e32 v7, 0x7f8, v13
	v_add_u32_e32 v12, 0x180, v12
	v_and_b32_e32 v26, 0x7ff, v6
	v_lshlrev_b32_e32 v124, 2, v7
	v_cmp_le_i32_e32 vcc, s42, v12
	v_cmp_ne_u32_e64 s[20:21], 0, v26
	v_add_u32_e32 v28, -2, v6
	v_lshl_add_u64 v[24:25], s[24:25], 0, v[124:125]
	v_cmp_lt_u32_e64 s[16:17], 1, v26
	s_or_b64 s[40:41], vcc, s[40:41]
	s_andn2_b64 s[100:101], exec, vcc
	v_subbrev_co_u32_e64 v37, vcc, 0, v6, s[20:21]
	v_cndmask_b32_e64 v36, v6, v28, s[16:17]
	v_add_co_u32_e32 v28, vcc, s81, v24
	v_mul_hi_i32_i24_e32 v23, 0xb000, v6
	v_mul_i32_i24_e32 v22, 0xb000, v6
	v_addc_co_u32_e32 v29, vcc, 0, v25, vcc
	v_mov_b32_e32 v11, v125
	v_lshlrev_b32_e32 v10, 1, v7
	v_lshl_add_u64 v[22:23], s[54:55], 0, v[22:23]
	v_add_co_u32_e32 v32, vcc, s74, v24
	v_mov_b64_e32 v[8:9], s[54:55]
	v_ashrrev_i32_e32 v7, 31, v6
	v_lshl_add_u64 v[30:31], v[22:23], 0, v[10:11]
	v_addc_co_u32_e32 v33, vcc, 0, v25, vcc
	v_cndmask_b32_e64 v62, 0, 1.0, s[16:17]
	v_lshlrev_b64 v[26:27], 12, v[6:7]
	v_mad_i64_i32 v[46:47], s[16:17], v36, s73, v[8:9]
	v_add_co_u32_e32 v42, vcc, s81, v30
	v_lshl_add_u64 v[6:7], v[24:25], 0, s[62:63]
	v_lshl_add_u64 v[34:35], v[24:25], 0, s[64:65]
	v_lshl_add_u64 v[38:39], s[60:61], 0, v[26:27]
	v_mad_i64_i32 v[48:49], s[16:17], v37, s73, v[8:9]
	v_addc_co_u32_e32 v43, vcc, 0, v31, vcc
	v_lshl_add_u64 v[54:55], v[46:47], 0, v[10:11]
	global_load_dwordx4 v[14:17], v124, s[24:25] offset:16
	global_load_dwordx4 v[18:21], v124, s[24:25]
	global_load_dwordx4 v[22:25], v[28:29], off
	s_nop 0
	global_load_dwordx4 v[26:29], v[6:7], off offset:16
	v_lshl_add_u64 v[66:67], v[38:39], 0, v[10:11]
	global_load_dwordx4 v[6:9], v[30:31], off
	s_nop 0
	global_load_dwordx4 v[30:33], v[32:33], off
	s_nop 0
	global_load_dwordx4 v[34:37], v[34:35], off offset:16
	s_nop 0
	global_load_dwordx4 v[38:41], v[42:43], off offset:-4096
	s_nop 0
	global_load_dwordx4 v[42:45], v[42:43], off
	v_lshl_add_u64 v[10:11], v[48:49], 0, v[10:11]
	global_load_dwordx4 v[46:49], v[54:55], off
	global_load_dwordx4 v[50:53], v[10:11], off
	v_add_co_u32_e32 v54, vcc, s83, v54
	v_cndmask_b32_e64 v64, 0, 1.0, s[20:21]
	s_nop 0
	v_addc_co_u32_e32 v55, vcc, 0, v55, vcc
	v_add_co_u32_e32 v10, vcc, s83, v10
	v_add_u32_e32 v13, 0xc00, v13
	s_nop 0
	v_addc_co_u32_e32 v11, vcc, 0, v11, vcc
	global_load_dwordx4 v[54:57], v[54:55], off
	s_nop 0
	global_load_dwordx4 v[58:61], v[10:11], off
	v_ashrrev_i32_e32 v148, 8, v12
	v_and_b32_e32 v149, 0x7f8, v13
	v_add_u32_e32 v12, 0x180, v12
	v_and_b32_e32 v94, 0x7ff, v148
	v_lshlrev_b32_e32 v124, 2, v149
	v_cmp_le_i32_e32 vcc, s42, v12
	v_cmp_ne_u32_e64 s[20:21], 0, v94
	v_add_u32_e32 v96, -2, v148
	v_lshl_add_u64 v[92:93], s[24:25], 0, v[124:125]
	v_cmp_lt_u32_e64 s[16:17], 1, v94
	s_or_b64 s[40:41], vcc, s[40:41]
	v_subbrev_co_u32_e64 v105, vcc, 0, v148, s[20:21]
	v_cndmask_b32_e64 v104, v148, v96, s[16:17]
	v_add_co_u32_e32 v96, vcc, s81, v92
	v_mul_hi_i32_i24_e32 v91, 0xb000, v148
	v_mul_i32_i24_e32 v90, 0xb000, v148
	v_addc_co_u32_e32 v97, vcc, 0, v93, vcc
	v_mov_b32_e32 v11, v125
	v_lshlrev_b32_e32 v10, 1, v149
	v_lshl_add_u64 v[90:91], s[54:55], 0, v[90:91]
	v_add_co_u32_e32 v100, vcc, s74, v92
	v_mov_b64_e32 v[150:151], s[54:55]
	v_ashrrev_i32_e32 v149, 31, v148
	v_lshl_add_u64 v[98:99], v[90:91], 0, v[10:11]
	v_addc_co_u32_e32 v101, vcc, 0, v93, vcc
	v_cndmask_b32_e64 v138, 0, 1.0, s[16:17]
	v_lshlrev_b64 v[94:95], 12, v[148:149]
	v_mad_i64_i32 v[114:115], s[16:17], v104, s73, v[150:151]
	v_add_co_u32_e32 v110, vcc, s81, v98
	v_lshl_add_u64 v[148:149], v[92:93], 0, s[62:63]
	v_lshl_add_u64 v[102:103], v[92:93], 0, s[64:65]
	v_lshl_add_u64 v[106:107], s[60:61], 0, v[94:95]
	v_mad_i64_i32 v[116:117], s[16:17], v105, s73, v[150:151]
	v_addc_co_u32_e32 v111, vcc, 0, v99, vcc
	v_lshl_add_u64 v[130:131], v[114:115], 0, v[10:11]
	global_load_dwordx4 v[82:85], v124, s[24:25] offset:16
	global_load_dwordx4 v[86:89], v124, s[24:25]
	global_load_dwordx4 v[90:93], v[96:97], off
	s_nop 0
	global_load_dwordx4 v[94:97], v[148:149], off offset:16
	v_lshl_add_u64 v[142:143], v[106:107], 0, v[10:11]
	global_load_dwordx4 v[148:151], v[98:99], off
	s_nop 0
	global_load_dwordx4 v[98:101], v[100:101], off
	s_nop 0
	global_load_dwordx4 v[102:105], v[102:103], off offset:16
	s_nop 0
	global_load_dwordx4 v[106:109], v[110:111], off offset:-4096
	s_nop 0
	global_load_dwordx4 v[110:113], v[110:111], off
	v_lshl_add_u64 v[10:11], v[116:117], 0, v[10:11]
	global_load_dwordx4 v[114:117], v[130:131], off
	global_load_dwordx4 v[118:121], v[10:11], off
	v_add_co_u32_e32 v130, vcc, s83, v130
	v_cndmask_b32_e64 v140, 0, 1.0, s[20:21]
	s_nop 0
	v_addc_co_u32_e32 v131, vcc, 0, v131, vcc
	v_add_co_u32_e32 v10, vcc, s83, v10
	v_add_u32_e32 v13, 0xc00, v13
	s_nop 0
	v_addc_co_u32_e32 v11, vcc, 0, v11, vcc
	global_load_dwordx4 v[130:133], v[130:131], off
	s_nop 0
	global_load_dwordx4 v[134:137], v[10:11], off
	s_waitcnt vmcnt(25)
	v_pk_mul_f32 v[16:17], v[16:17], v[62:63] op_sel_hi:[1,0]
	s_waitcnt vmcnt(24)
	v_pk_mul_f32 v[10:11], v[20:21], v[62:63] op_sel_hi:[1,0]
	v_pk_mul_f32 v[18:19], v[18:19], v[62:63] op_sel_hi:[1,0]
	v_pk_mul_f32 v[14:15], v[14:15], v[62:63] op_sel_hi:[1,0]
	s_waitcnt vmcnt(23)
	v_pk_mul_f32 v[20:21], v[64:65], v[24:25] op_sel_hi:[0,1]
	v_pk_mul_f32 v[22:23], v[64:65], v[22:23] op_sel_hi:[0,1]
	s_waitcnt vmcnt(22)
	v_pk_mul_f32 v[24:25], v[64:65], v[28:29] op_sel_hi:[0,1]
	v_pk_mul_f32 v[26:27], v[64:65], v[26:27] op_sel_hi:[0,1]
	s_waitcnt vmcnt(21)
	v_lshlrev_b32_e32 v28, 16, v6
	v_and_b32_e32 v29, 0xffff0000, v6
	v_lshlrev_b32_e32 v6, 16, v7
	v_and_b32_e32 v7, 0xffff0000, v7
	v_lshlrev_b32_e32 v62, 16, v8
	v_and_b32_e32 v63, 0xffff0000, v8
	v_lshlrev_b32_e32 v8, 16, v9
	v_and_b32_e32 v9, 0xffff0000, v9
	s_waitcnt vmcnt(18)
	v_lshlrev_b32_e32 v64, 16, v38
	v_and_b32_e32 v65, 0xffff0000, v38
	v_lshlrev_b32_e32 v38, 16, v39
	v_and_b32_e32 v39, 0xffff0000, v39
	v_lshlrev_b32_e32 v70, 16, v40
	v_and_b32_e32 v71, 0xffff0000, v40
	v_lshlrev_b32_e32 v40, 16, v41
	v_and_b32_e32 v41, 0xffff0000, v41
	s_waitcnt vmcnt(16)
	v_lshlrev_b32_e32 v74, 16, v46
	v_and_b32_e32 v75, 0xffff0000, v46
	v_lshlrev_b32_e32 v46, 16, v47
	v_and_b32_e32 v47, 0xffff0000, v47
	v_pk_mul_f32 v[6:7], v[6:7], v[38:39]
	v_lshlrev_b32_e32 v38, 16, v48
	v_and_b32_e32 v39, 0xffff0000, v48
	v_lshlrev_b32_e32 v48, 16, v49
	v_and_b32_e32 v49, 0xffff0000, v49
	v_pk_mul_f32 v[8:9], v[8:9], v[40:41]
	s_waitcnt vmcnt(14)
	v_lshlrev_b32_e32 v40, 16, v54
	v_and_b32_e32 v41, 0xffff0000, v54
	v_lshlrev_b32_e32 v54, 16, v55
	v_and_b32_e32 v55, 0xffff0000, v55
	v_lshlrev_b32_e32 v78, 16, v56
	v_and_b32_e32 v79, 0xffff0000, v56
	v_lshlrev_b32_e32 v56, 16, v57
	v_and_b32_e32 v57, 0xffff0000, v57
	v_lshlrev_b32_e32 v76, 16, v50
	v_and_b32_e32 v77, 0xffff0000, v50
	v_pk_mul_f32 v[28:29], v[28:29], v[64:65]
	v_lshlrev_b32_e32 v50, 16, v51
	v_and_b32_e32 v51, 0xffff0000, v51
	v_lshlrev_b32_e32 v64, 16, v52
	v_and_b32_e32 v65, 0xffff0000, v52
	v_pk_mul_f32 v[62:63], v[62:63], v[70:71]
	v_lshlrev_b32_e32 v52, 16, v53
	v_and_b32_e32 v53, 0xffff0000, v53
	s_waitcnt vmcnt(13)
	v_lshlrev_b32_e32 v70, 16, v58
	v_and_b32_e32 v71, 0xffff0000, v58
	v_lshlrev_b32_e32 v58, 16, v59
	v_and_b32_e32 v59, 0xffff0000, v59
	v_lshlrev_b32_e32 v80, 16, v60
	v_and_b32_e32 v81, 0xffff0000, v60
	v_lshlrev_b32_e32 v60, 16, v61
	v_and_b32_e32 v61, 0xffff0000, v61
	v_pk_mul_f32 v[40:41], v[74:75], v[40:41]
	v_pk_mul_f32 v[46:47], v[46:47], v[54:55]
	v_pk_mul_f32 v[38:39], v[38:39], v[78:79]
	v_pk_mul_f32 v[48:49], v[48:49], v[56:57]
	v_pk_mul_f32 v[70:71], v[76:77], v[70:71]
	v_pk_mul_f32 v[50:51], v[50:51], v[58:59]
	v_pk_mul_f32 v[54:55], v[64:65], v[80:81]
	v_pk_mul_f32 v[52:53], v[52:53], v[60:61]
	v_pk_fma_f32 v[18:19], v[40:41], v[18:19], 0 op_sel_hi:[1,1,0]
	v_pk_fma_f32 v[10:11], v[46:47], v[10:11], 0 op_sel_hi:[1,1,0]
	v_pk_fma_f32 v[14:15], v[38:39], v[14:15], 0 op_sel_hi:[1,1,0]
	v_pk_fma_f32 v[16:17], v[48:49], v[16:17], 0 op_sel_hi:[1,1,0]
	v_pk_fma_f32 v[18:19], v[22:23], v[70:71], v[18:19]
	v_pk_fma_f32 v[10:11], v[20:21], v[50:51], v[10:11]
	v_pk_fma_f32 v[14:15], v[26:27], v[54:55], v[14:15]
	v_pk_fma_f32 v[16:17], v[24:25], v[52:53], v[16:17]
	v_lshlrev_b32_e32 v68, 16, v42
	v_and_b32_e32 v69, 0xffff0000, v42
	v_lshlrev_b32_e32 v42, 16, v43
	v_and_b32_e32 v43, 0xffff0000, v43
	v_lshlrev_b32_e32 v72, 16, v44
	v_and_b32_e32 v73, 0xffff0000, v44
	v_lshlrev_b32_e32 v44, 16, v45
	v_and_b32_e32 v45, 0xffff0000, v45
	v_pk_fma_f32 v[18:19], v[30:31], v[28:29], v[18:19]
	v_pk_fma_f32 v[6:7], v[32:33], v[6:7], v[10:11]
	v_pk_fma_f32 v[10:11], v[34:35], v[62:63], v[14:15]
	v_pk_fma_f32 v[8:9], v[36:37], v[8:9], v[16:17]
	v_pk_mul_f32 v[14:15], v[18:19], v[68:69]
	v_pk_mul_f32 v[16:17], v[6:7], v[42:43]
	v_pk_mul_f32 v[10:11], v[10:11], v[72:73]
	v_pk_mul_f32 v[18:19], v[8:9], v[44:45]
	v_cvt_pk_bf16_f32 v6, v14, v15
	v_cvt_pk_bf16_f32 v7, v16, v17
	v_cvt_pk_bf16_f32 v8, v10, v11
	v_cvt_pk_bf16_f32 v9, v18, v19
	global_store_dwordx4 v[66:67], v[6:9], off
	s_mov_b64 s[98:99], exec
	s_mov_b64 exec, s[100:101]
	s_waitcnt vmcnt(13)
	v_pk_mul_f32 v[84:85], v[84:85], v[138:139] op_sel_hi:[1,0]
	s_waitcnt vmcnt(12)
	v_pk_mul_f32 v[10:11], v[88:89], v[138:139] op_sel_hi:[1,0]
	v_pk_mul_f32 v[86:87], v[86:87], v[138:139] op_sel_hi:[1,0]
	v_pk_mul_f32 v[82:83], v[82:83], v[138:139] op_sel_hi:[1,0]
	s_waitcnt vmcnt(11)
	v_pk_mul_f32 v[88:89], v[140:141], v[92:93] op_sel_hi:[0,1]
	v_pk_mul_f32 v[90:91], v[140:141], v[90:91] op_sel_hi:[0,1]
	s_waitcnt vmcnt(10)
	v_pk_mul_f32 v[92:93], v[140:141], v[96:97] op_sel_hi:[0,1]
	v_pk_mul_f32 v[94:95], v[140:141], v[94:95] op_sel_hi:[0,1]
	s_waitcnt vmcnt(9)
	v_lshlrev_b32_e32 v96, 16, v148
	v_and_b32_e32 v97, 0xffff0000, v148
	v_lshlrev_b32_e32 v148, 16, v149
	v_and_b32_e32 v149, 0xffff0000, v149
	v_lshlrev_b32_e32 v138, 16, v150
	v_and_b32_e32 v139, 0xffff0000, v150
	v_lshlrev_b32_e32 v150, 16, v151
	v_and_b32_e32 v151, 0xffff0000, v151
	s_waitcnt vmcnt(6)
	v_lshlrev_b32_e32 v140, 16, v106
	v_and_b32_e32 v141, 0xffff0000, v106
	v_lshlrev_b32_e32 v106, 16, v107
	v_and_b32_e32 v107, 0xffff0000, v107
	v_lshlrev_b32_e32 v70, 16, v108
	v_and_b32_e32 v71, 0xffff0000, v108
	v_lshlrev_b32_e32 v108, 16, v109
	v_and_b32_e32 v109, 0xffff0000, v109
	s_waitcnt vmcnt(4)
	v_lshlrev_b32_e32 v74, 16, v114
	v_and_b32_e32 v75, 0xffff0000, v114
	v_lshlrev_b32_e32 v114, 16, v115
	v_and_b32_e32 v115, 0xffff0000, v115
	v_pk_mul_f32 v[148:149], v[148:149], v[106:107]
	v_lshlrev_b32_e32 v106, 16, v116
	v_and_b32_e32 v107, 0xffff0000, v116
	v_lshlrev_b32_e32 v116, 16, v117
	v_and_b32_e32 v117, 0xffff0000, v117
	v_pk_mul_f32 v[150:151], v[150:151], v[108:109]
	s_waitcnt vmcnt(2)
	v_lshlrev_b32_e32 v108, 16, v130
	v_and_b32_e32 v109, 0xffff0000, v130
	v_lshlrev_b32_e32 v130, 16, v131
	v_and_b32_e32 v131, 0xffff0000, v131
	v_lshlrev_b32_e32 v78, 16, v132
	v_and_b32_e32 v79, 0xffff0000, v132
	v_lshlrev_b32_e32 v132, 16, v133
	v_and_b32_e32 v133, 0xffff0000, v133
	v_lshlrev_b32_e32 v76, 16, v118
	v_and_b32_e32 v77, 0xffff0000, v118
	v_pk_mul_f32 v[96:97], v[96:97], v[140:141]
	v_lshlrev_b32_e32 v118, 16, v119
	v_and_b32_e32 v119, 0xffff0000, v119
	v_lshlrev_b32_e32 v140, 16, v120
	v_and_b32_e32 v141, 0xffff0000, v120
	v_pk_mul_f32 v[138:139], v[138:139], v[70:71]
	v_lshlrev_b32_e32 v120, 16, v121
	v_and_b32_e32 v121, 0xffff0000, v121
	s_waitcnt vmcnt(1)
	v_lshlrev_b32_e32 v70, 16, v134
	v_and_b32_e32 v71, 0xffff0000, v134
	v_lshlrev_b32_e32 v134, 16, v135
	v_and_b32_e32 v135, 0xffff0000, v135
	v_lshlrev_b32_e32 v80, 16, v136
	v_and_b32_e32 v81, 0xffff0000, v136
	v_lshlrev_b32_e32 v136, 16, v137
	v_and_b32_e32 v137, 0xffff0000, v137
	v_pk_mul_f32 v[108:109], v[74:75], v[108:109]
	v_pk_mul_f32 v[114:115], v[114:115], v[130:131]
	v_pk_mul_f32 v[106:107], v[106:107], v[78:79]
	v_pk_mul_f32 v[116:117], v[116:117], v[132:133]
	v_pk_mul_f32 v[70:71], v[76:77], v[70:71]
	v_pk_mul_f32 v[118:119], v[118:119], v[134:135]
	v_pk_mul_f32 v[130:131], v[140:141], v[80:81]
	v_pk_mul_f32 v[120:121], v[120:121], v[136:137]
	v_pk_fma_f32 v[86:87], v[108:109], v[86:87], 0 op_sel_hi:[1,1,0]
	v_pk_fma_f32 v[10:11], v[114:115], v[10:11], 0 op_sel_hi:[1,1,0]
	v_pk_fma_f32 v[82:83], v[106:107], v[82:83], 0 op_sel_hi:[1,1,0]
	v_pk_fma_f32 v[84:85], v[116:117], v[84:85], 0 op_sel_hi:[1,1,0]
	v_pk_fma_f32 v[86:87], v[90:91], v[70:71], v[86:87]
	v_pk_fma_f32 v[10:11], v[88:89], v[118:119], v[10:11]
	v_pk_fma_f32 v[82:83], v[94:95], v[130:131], v[82:83]
	v_pk_fma_f32 v[84:85], v[92:93], v[120:121], v[84:85]
	v_lshlrev_b32_e32 v68, 16, v110
	v_and_b32_e32 v69, 0xffff0000, v110
	v_lshlrev_b32_e32 v110, 16, v111
	v_and_b32_e32 v111, 0xffff0000, v111
	v_lshlrev_b32_e32 v72, 16, v112
	v_and_b32_e32 v73, 0xffff0000, v112
	v_lshlrev_b32_e32 v112, 16, v113
	v_and_b32_e32 v113, 0xffff0000, v113
	v_pk_fma_f32 v[86:87], v[98:99], v[96:97], v[86:87]
	v_pk_fma_f32 v[148:149], v[100:101], v[148:149], v[10:11]
	v_pk_fma_f32 v[10:11], v[102:103], v[138:139], v[82:83]
	v_pk_fma_f32 v[150:151], v[104:105], v[150:151], v[84:85]
	v_pk_mul_f32 v[82:83], v[86:87], v[68:69]
	v_pk_mul_f32 v[84:85], v[148:149], v[110:111]
	v_pk_mul_f32 v[10:11], v[10:11], v[72:73]
	v_pk_mul_f32 v[86:87], v[150:151], v[112:113]
	v_cvt_pk_bf16_f32 v148, v82, v83
	v_cvt_pk_bf16_f32 v149, v84, v85
	v_cvt_pk_bf16_f32 v150, v10, v11
	v_cvt_pk_bf16_f32 v151, v86, v87
	global_store_dwordx4 v[142:143], v[148:151], off
	s_mov_b64 exec, s[98:99]
	s_andn2_b64 exec, exec, s[40:41]
	s_cbranch_execnz .LBB0_555
